# speedup vs baseline: 1.0116x; 1.0116x over previous
; #define MK_TID(wave_) ((wave_) * 64 + MK_LANE())
; #define ALAS __attribute__((address_space(3)))
; #define tid MK_TID(wave)
; template <int MODE> ...
;     ...
;     int tid_ = MK_TID(wave_s); asm volatile("" : "+v"(tid_));
;     const int tid = tid_, lane = tid & 63, r32 = lane & 31, hi = lane >> 5;
;     const int wid = __builtin_amdgcn_readfirstlane(tid >> 6);
;     const int q0 = qb * 256, qw = q0 + 32 * wid;
;     const int thi = 4 * qb + 3, tlo = (MODE == 2) ? (qb ? 4 * qb - 2 : 0) : 0, n = thi - tlo + 1;
;     const unsigned lds0 = (unsigned)(uintptr_t)shm;
;     ALAS float* wsf = (ALAS float*)(shm + L_WS) + wid * 64;
;     ...
;     ATT_DMA_TILE(ATT_TILE_OF(0), 0, 0);
;     bf16x8 qr[ND0];
; #pragma unroll
;     for (int d0 = 0; d0 < ND0; ++d0) qr[d0] = *(const bf16x8*)(Qp + (size_t)(qw + r32) * pitchQ + d0 * 16 + hi * 8);
;     f32x16 o[NDB];
; #pragma unroll
;     for (int db = 0; db < NDB; ++db) o[db] = f32x16{};
;     float mhat = -1e30f, lsum = 0.f, Rp = 0.f;
;     u32x4 pw0 = {}, pw1 = {}, pw2 = {}, pw3 = {};
;     const bool late = (MODE != 1) && wid >= 4; bool pend = false; int pvslot = 0;
; __global__ void __launch_bounds__(NTHREADS, 2) mega_fwd(Params P) {
;     ...
;                     const int qb = 31 - (item >> 3), h = item & 7;
;                     att::attn_unit<1>(QS + h * 128, 1024, KS + h * 128, 1024, VS + h * 128, 1024, OCAT + 1024 + h * 128, 2048, qb, 0.f, lds, wave);
;     ...
;                     __syncthreads();
;     ...
;                 } else {
;     ...
;                     const int i2 = item - 256, qb = 31 - (i2 >> 4), hm = i2 & 15, h = hm >> 1, m = hm & 1;
;                     att::attn_unit<0>(QA + h * 128 + m * 64, 1024, KA + h * 128 + m * 64, 1024, VA + h * 128, 1024, (m ? OA2 : OA1) + h * 128, 1024, qb, 0.f, lds, wave);
.LBB0_227:
	s_or_b64 exec, exec, s[0:1]
	v_mov_b32_e32 v0, s50
	s_waitcnt lgkmcnt(0)
	s_barrier
	ds_read_b32 v0, v0
	s_movk_i32 s0, 0x2ff
	s_waitcnt lgkmcnt(0)
	v_cmp_lt_i32_e32 vcc, s0, v0
	v_readfirstlane_b32 s16, v0
	s_mov_b64 s[0:1], -1
	s_cbranch_vccnz .LBB0_222
	s_cmpk_gt_i32 s16, 0xff
	s_cbranch_scc0 .LBB0_266
	s_add_i32 s0, s16, 0xffffff00
	s_lshr_b32 s10, s0, 4
	s_lshl_b32 s0, s16, 6
	s_and_b32 s18, s0, 0x380
	s_sub_i32 s6, 31, s10
	s_and_b32 s19, s16, 1
	s_lshl_b32 s4, s18, 1
	s_add_u32 s0, s48, s4
	s_addc_u32 s1, s49, 0
	s_lshl_b32 s5, s19, 7
	s_add_u32 s0, s0, s5
	s_addc_u32 s1, s1, 0
	v_readlane_b32 s7, v255, 4
	s_add_u32 s7, s7, s4
	v_readlane_b32 s11, v255, 5
	s_addc_u32 s11, s11, 0
	s_add_u32 s12, s7, s5
	s_addc_u32 s13, s11, 0
	v_readlane_b32 s5, v255, 0
	v_mbcnt_lo_u32_b32 v0, -1, 0
	v_mbcnt_hi_u32_b32 v0, -1, v0
	s_add_u32 s22, s5, s4
	v_add_u32_e32 v4, s3, v0
	v_readlane_b32 s4, v255, 1
	s_addc_u32 s23, s4, 0
	v_readfirstlane_b32 s7, v4
	s_ashr_i32 s20, s7, 6
	v_and_b32_e32 v134, 63, v4
	s_lshl_b32 s4, s20, 3
	v_lshlrev_b32_e32 v0, 11, v134
	s_ashr_i32 s5, s4, 31
	v_lshl_add_u64 v[2:3], s[12:13], 0, v[0:1]
	s_lshl_b64 s[28:29], s[4:5], 1
	s_lshl_b32 s21, s20, 10
	v_lshl_add_u64 v[2:3], v[2:3], 0, s[28:29]
	s_add_i32 s26, s21, 0
	s_mov_b32 s4, m0
	s_mov_b32 m0, s26
	s_nop 0
	global_load_lds_dwordx4 v[2:3], off
	s_mov_b32 m0, s4
	s_lshl_b32 s4, s20, 4
	v_bfe_u32 v0, v4, 2, 4
	v_and_or_b32 v5, s4, 48, v0
	s_ashr_i32 s4, s7, 3
	s_andn2_b32 s4, s4, 31
	v_lshlrev_b32_e32 v0, 11, v5
	s_ashr_i32 s5, s4, 31
	v_lshlrev_b32_e32 v135, 3, v4
	v_lshl_add_u64 v[2:3], s[22:23], 0, v[0:1]
	s_lshl_b64 s[30:31], s[4:5], 1
	v_and_b32_e32 v194, 24, v135
	v_lshl_add_u64 v[2:3], v[2:3], 0, s[30:31]
	v_lshlrev_b32_e32 v0, 1, v194
	s_add_i32 s11, 0, 0x8000
	v_lshl_add_u64 v[2:3], v[2:3], 0, v[0:1]
	s_add_i32 s4, s21, s11
	s_mov_b32 s5, m0
	s_mov_b32 m0, s4
	s_nop 0
	global_load_lds_dwordx4 v[2:3], off
	s_mov_b32 m0, s5
	s_add_i32 s14, 0, 0xa000
	v_lshl_add_u64 v[2:3], v[2:3], 0, s[92:93]
	s_add_i32 s21, s21, s14
	s_mov_b32 s4, m0
	s_mov_b32 m0, s21
	s_nop 0
	global_load_lds_dwordx4 v[2:3], off
	s_mov_b32 m0, s4
	s_lshl_b32 s17, s20, 5
	s_lshl_b32 s4, s6, 8
	v_and_b32_e32 v136, 31, v4
	s_add_i32 s17, s17, s4
	v_or_b32_e32 v130, s17, v136
	v_ashrrev_i32_e32 v131, 31, v130
	v_bfe_u32 v137, v4, 5, 1
	v_lshlrev_b64 v[2:3], 11, v[130:131]
	v_lshl_add_u64 v[2:3], s[0:1], 0, v[2:3]
	v_lshlrev_b32_e32 v128, 4, v137
	v_mov_b32_e32 v129, v1
	v_lshl_add_u64 v[2:3], v[2:3], 0, v[128:129]
	global_load_dwordx4 v[124:127], v[2:3], off
	global_load_dwordx4 v[120:123], v[2:3], off offset:32
	global_load_dwordx4 v[116:119], v[2:3], off offset:64
	global_load_dwordx4 v[112:115], v[2:3], off offset:96
	s_and_b32 s15, s7, 0x3fffffc0
	s_lshl_b32 s0, s15, 2
	s_add_i32 s21, s0, 0
	s_add_i32 s21, s21, 0x14000
	s_cmp_gt_i32 s20, 3
	s_cselect_b64 s[4:5], -1, 0
	s_cmp_lt_i32 s20, 4
	s_cselect_b64 s[6:7], -1, 0
	s_add_u32 s12, s12, s28
	s_addc_u32 s13, s13, s29
	s_add_u32 s0, s22, s30
	s_addc_u32 s1, s23, s31
	v_lshl_add_u64 v[132:133], s[0:1], 0, v[0:1]
	v_lshlrev_b32_e32 v0, 1, v4
	v_and_b32_e32 v200, 32, v0
	v_lshlrev_b32_e32 v2, 4, v4
	v_add3_u32 v0, 0, v200, v194
	v_lshlrev_b32_e32 v210, 8, v137
	v_and_b32_e32 v211, 0xc0, v2
	v_add3_u32 v143, v0, v210, v211
	v_lshlrev_b32_e32 v129, 10, v137
	v_lshlrev_b32_e32 v0, 4, v136
	s_lshl_b32 s10, s10, 2
	v_add3_u32 v144, 0, v129, v0
	s_sub_i32 s30, 0, s10
	v_or_b32_e32 v0, v210, v211
	v_readlane_b32 s10, v254, 6
	s_waitcnt vmcnt(0) lgkmcnt(0)
	s_barrier
; #define ATT_WAIT_BAR() asm volatile("s_waitcnt vmcnt(0) lgkmcnt(0)\n\ts_barrier" ::: "memory")
; template <int MODE> ...
;     ...
;     f32x16 o[NDB];
; #pragma unroll
;     for (int db = 0; db < NDB; ++db) o[db] = f32x16{};
;     float mhat = -1e30f, lsum = 0.f, Rp = 0.f;
;     u32x4 pw0 = {}, pw1 = {}, pw2 = {}, pw3 = {};
;     const bool late = (MODE != 1) && wid >= 4; bool pend = false; int pvslot = 0;
;     constexpr int NVB = NDB * 4 / 8;
;     ...
;     ATT_WAIT_BAR();
; #pragma unroll
;     for (int d0 = 0; d0 < ND0; ++d0) asm volatile("" : "+v"(qr[d0]));
	v_mov_b32_e32 v14, v1
	v_mov_b32_e32 v15, v1
	v_add_u32_e32 v146, s10, v0
	v_readlane_b32 s10, v254, 7
	v_or_b32_e32 v145, 64, v5
	v_add_u32_e32 v166, s14, v0
	v_add_u32_e32 v215, s10, v0
	v_readlane_b32 s10, v254, 8
	v_add_u32_e32 v180, s51, v0
	v_add_u32_e32 v181, s33, v0
	v_add_u32_e32 v214, s10, v0
	v_readlane_b32 s10, v254, 9
	v_add_u32_e32 v182, s11, v0
	v_mov_b32_e32 v2, v1
	v_add_u32_e32 v201, s10, v0
	v_readlane_b32 s10, v254, 10
	v_mov_b32_e32 v3, v1
	v_mov_b32_e32 v4, v1
	v_add_u32_e32 v252, s10, v0
	v_readlane_b32 s10, v254, 11
	v_mov_b32_e32 v5, v1
	v_mov_b32_e32 v6, v1
	v_add_u32_e32 v152, s10, v0
	v_readlane_b32 s10, v254, 12
	v_mov_b32_e32 v7, v1
	v_mov_b32_e32 v8, v1
	v_add_u32_e32 v153, s10, v0
	v_readlane_b32 s10, v254, 13
	v_mov_b32_e32 v9, v1
	v_mov_b32_e32 v10, v1
	v_add_u32_e32 v154, s10, v0
	v_readlane_b32 s10, v254, 14
	v_mov_b32_e32 v11, v1
	v_mov_b32_e32 v12, v1
	v_add_u32_e32 v155, s10, v0
	v_readlane_b32 s10, v254, 15
	v_mov_b32_e32 v13, v1
	s_mov_b32 s25, 1
	v_add_u32_e32 v156, s10, v0
	v_readlane_b32 s10, v254, 16
	s_or_b32 s27, s17, 31
	v_cmp_gt_u32_e64 s[0:1], 32, v134
	v_add_u32_e32 v157, s10, v0
	v_readlane_b32 s10, v254, 17
	v_lshl_add_u32 v131, v136, 2, s21
	s_mov_b32 s28, 0
	v_add_u32_e32 v162, s10, v0
	v_readlane_b32 s10, v254, 18
	s_add_i32 s31, s26, 0xc000
	v_or_b32_e32 v147, v194, v200
	v_add_u32_e32 v163, s10, v0
	v_readlane_b32 s10, v254, 19
	v_mov_b32_e32 v142, 0
	v_mov_b32_e32 v185, 0xf149f2ca
	v_add_u32_e32 v164, s10, v0
	v_readlane_b32 s10, v254, 20
	s_movk_i32 s29, 0xff81
	v_mov_b32_e32 v84, 0
	v_add_u32_e32 v165, s10, v0
	v_readlane_b32 s10, v255, 57
	v_mov_b32_e32 v85, 0
	v_mov_b32_e32 v86, 0
	v_add_u32_e32 v167, s10, v0
	v_readlane_b32 s10, v255, 58
	v_mov_b32_e32 v87, 0
	v_mov_b32_e32 v92, 0
	v_add_u32_e32 v168, s10, v0
	v_readlane_b32 s10, v255, 59
	v_mov_b32_e32 v93, 0
	v_mov_b32_e32 v94, 0
	v_add_u32_e32 v169, s10, v0
	v_readlane_b32 s10, v255, 60
	v_mov_b32_e32 v95, 0
	v_mov_b32_e32 v80, 0
	v_add_u32_e32 v170, s10, v0
	v_readlane_b32 s10, v255, 61
	v_mov_b32_e32 v81, 0
	v_mov_b32_e32 v82, 0
	v_add_u32_e32 v171, s10, v0
	v_readlane_b32 s10, v255, 62
	v_mov_b32_e32 v83, 0
	v_mov_b32_e32 v88, 0
	v_add_u32_e32 v172, s10, v0
	v_readlane_b32 s10, v255, 63
	v_mov_b32_e32 v89, 0
	v_mov_b32_e32 v90, 0
	v_add_u32_e32 v173, s10, v0
	v_readlane_b32 s10, v254, 0
	v_mov_b32_e32 v91, 0
	v_mov_b32_e32 v183, v130
	v_add_u32_e32 v174, s10, v0
	v_readlane_b32 s10, v254, 1
	s_mov_b32 s23, 0
	s_mov_b32 s22, 0
	v_add_u32_e32 v175, s10, v0
	v_readlane_b32 s10, v254, 2
	s_mov_b32 s24, 0
	s_waitcnt vmcnt(0)
	v_add_u32_e32 v176, s10, v0
	v_readlane_b32 s10, v254, 3
	s_nop 1
	v_add_u32_e32 v177, s10, v0
	v_readlane_b32 s10, v254, 4
	s_nop 1
	v_add_u32_e32 v178, s10, v0
	v_readlane_b32 s10, v254, 5
	s_nop 1
	v_add_u32_e32 v179, s10, v0
	v_mov_b32_e32 v0, v1
	v_mov_b64_e32 v[30:31], v[14:15]
	v_mov_b64_e32 v[46:47], v[14:15]
	v_mov_b64_e32 v[62:63], v[14:15]
	v_mov_b64_e32 v[78:79], v[14:15]
	s_mov_b64 s[10:11], 0
	v_mov_b64_e32 v[28:29], v[12:13]
	v_mov_b64_e32 v[26:27], v[10:11]
	v_mov_b64_e32 v[24:25], v[8:9]
	v_mov_b64_e32 v[22:23], v[6:7]
	v_mov_b64_e32 v[20:21], v[4:5]
	v_mov_b64_e32 v[18:19], v[2:3]
	v_mov_b64_e32 v[16:17], v[0:1]
	v_mov_b64_e32 v[44:45], v[12:13]
	v_mov_b64_e32 v[42:43], v[10:11]
	v_mov_b64_e32 v[40:41], v[8:9]
	v_mov_b64_e32 v[38:39], v[6:7]
	v_mov_b64_e32 v[36:37], v[4:5]
	v_mov_b64_e32 v[34:35], v[2:3]
	v_mov_b64_e32 v[32:33], v[0:1]
	v_mov_b64_e32 v[60:61], v[12:13]
	v_mov_b64_e32 v[58:59], v[10:11]
	v_mov_b64_e32 v[56:57], v[8:9]
	v_mov_b64_e32 v[54:55], v[6:7]
	v_mov_b64_e32 v[52:53], v[4:5]
	v_mov_b64_e32 v[50:51], v[2:3]
	v_mov_b64_e32 v[48:49], v[0:1]
	v_mov_b64_e32 v[76:77], v[12:13]
	v_mov_b64_e32 v[74:75], v[10:11]
	v_mov_b64_e32 v[72:73], v[8:9]
	v_mov_b64_e32 v[70:71], v[6:7]
	v_mov_b64_e32 v[68:69], v[4:5]
	v_mov_b64_e32 v[66:67], v[2:3]
	v_mov_b64_e32 v[64:65], v[0:1]

; template <int MODE> ...
;     ...
;     if (late && pend) { ATT_PV(pvslot); }
;     asm volatile("s_waitcnt lgkmcnt(0)\n\ts_barrier" ::: "memory");
.LBB0_261:
	s_waitcnt vmcnt(0) lgkmcnt(0)
	s_barrier
	s_and_b64 s[4:5], s[4:5], s[10:11]
	s_and_b64 vcc, exec, s[4:5]
	s_cbranch_vccz .LBB0_263
	s_lshl_b32 s4, s22, 14
	s_add_i32 s4, s4, 0
	v_add3_u32 v0, s4, v200, v194
	v_add3_u32 v0, v0, v210, v211
	ds_read_b64_tr_b16 v[2:3], v0 offset:32768
	ds_read_b64_tr_b16 v[4:5], v0 offset:33280
	ds_read_b64_tr_b16 v[6:7], v0 offset:33792
	ds_read_b64_tr_b16 v[8:9], v0 offset:34304
	ds_read_b64_tr_b16 v[10:11], v0 offset:34816
	ds_read_b64_tr_b16 v[12:13], v0 offset:35328
	ds_read_b64_tr_b16 v[96:97], v0 offset:35840
	ds_read_b64_tr_b16 v[98:99], v0 offset:36352
	ds_read_b64_tr_b16 v[100:101], v0 offset:36864
	ds_read_b64_tr_b16 v[102:103], v0 offset:37376
	ds_read_b64_tr_b16 v[104:105], v0 offset:37888
	ds_read_b64_tr_b16 v[106:107], v0 offset:38400
	ds_read_b64_tr_b16 v[108:109], v0 offset:38912
	ds_read_b64_tr_b16 v[110:111], v0 offset:39424
	ds_read_b64_tr_b16 v[112:113], v0 offset:39936
	ds_read_b64_tr_b16 v[114:115], v0 offset:40448
	ds_read_b64_tr_b16 v[116:117], v0 offset:40960
	ds_read_b64_tr_b16 v[118:119], v0 offset:41472
	ds_read_b64_tr_b16 v[120:121], v0 offset:41984
	ds_read_b64_tr_b16 v[122:123], v0 offset:42496
	ds_read_b64_tr_b16 v[124:125], v0 offset:43008
	ds_read_b64_tr_b16 v[126:127], v0 offset:43520
	ds_read_b64_tr_b16 v[138:139], v0 offset:44032
	ds_read_b64_tr_b16 v[140:141], v0 offset:44544
	ds_read_b64_tr_b16 v[144:145], v0 offset:45056
	ds_read_b64_tr_b16 v[146:147], v0 offset:45568
	ds_read_b64_tr_b16 v[148:149], v0 offset:46080
	ds_read_b64_tr_b16 v[150:151], v0 offset:46592
	ds_read_b64_tr_b16 v[152:153], v0 offset:47104
	ds_read_b64_tr_b16 v[154:155], v0 offset:47616
	ds_read_b64_tr_b16 v[156:157], v0 offset:48128
	ds_read_b64_tr_b16 v[158:159], v0 offset:48640
	s_waitcnt lgkmcnt(14)
	v_mfma_f32_32x32x16_bf16 v[64:79], v[80:83], v[2:5], v[64:79]
	v_mfma_f32_32x32x16_bf16 v[48:63], v[80:83], v[100:103], v[48:63]
	v_mfma_f32_32x32x16_bf16 v[64:79], v[88:91], v[6:9], v[64:79]
	v_mfma_f32_32x32x16_bf16 v[48:63], v[88:91], v[104:107], v[48:63]
	v_mfma_f32_32x32x16_bf16 v[64:79], v[84:87], v[10:13], v[64:79]
	v_mfma_f32_32x32x16_bf16 v[48:63], v[84:87], v[108:111], v[48:63]
	v_mfma_f32_32x32x16_bf16 v[64:79], v[92:95], v[96:99], v[64:79]
	v_mfma_f32_32x32x16_bf16 v[48:63], v[92:95], v[112:115], v[48:63]
	v_mfma_f32_32x32x16_bf16 v[32:47], v[80:83], v[116:119], v[32:47]
	s_waitcnt lgkmcnt(6)
	v_mfma_f32_32x32x16_bf16 v[16:31], v[80:83], v[144:147], v[16:31]
	v_mfma_f32_32x32x16_bf16 v[32:47], v[88:91], v[120:123], v[32:47]
	s_waitcnt lgkmcnt(4)
	v_mfma_f32_32x32x16_bf16 v[16:31], v[88:91], v[148:151], v[16:31]
	v_mfma_f32_32x32x16_bf16 v[32:47], v[84:87], v[124:127], v[32:47]
	s_waitcnt lgkmcnt(2)
	v_mfma_f32_32x32x16_bf16 v[16:31], v[84:87], v[152:155], v[16:31]
	v_mfma_f32_32x32x16_bf16 v[32:47], v[92:95], v[138:141], v[32:47]
	s_waitcnt lgkmcnt(0)
	v_mfma_f32_32x32x16_bf16 v[16:31], v[92:95], v[156:159], v[16:31]

; __device__ __forceinline__ float row_rstd(const float* part, int row, int fq) {
;     const f32x4* p = (const f32x4*)(part + (size_t)row * 32 + 8 * fq); const f32x4 a = p[0], b = p[1];
;     float s = ((a[0] + a[1]) + (a[2] + a[3])) + ((b[0] + b[1]) + (b[2] + b[3]));
; template <class Epi, class Sched, bool ALIGN_EPI = false, bool SP2 = false>
; __device__ __forceinline__ void gemm_phase(PG8_LAS unsigned char* lds, const Gemm g, const Sched& S, const Epi& E, const int wave_s) {
;     ...
;         for (int a = 0; a < 2; ++a)
; #pragma unroll
;             for (int b = 0; b < 2; ++b)
; #pragma unroll
;                 for (int m = 0; m < 4; ++m)
; #pragma unroll
;                     for (int n = 0; n < 2; ++n) acc[a][b][m][n] = (f32x4){0.f, 0.f, 0.f, 0.f};
;         cur = nxt; cA = nA; cB = nB; ++ui;
.LBB0_495:
	s_ashr_i32 s15, s14, 31
	s_lshl_b64 s[16:17], s[14:15], 20
	s_add_u32 s16, s46, s16
	s_addc_u32 s17, s47, s17
	s_and_b64 s[18:19], s[4:5], exec
	s_cselect_b32 s15, s17, s7
	s_cselect_b32 s40, s16, s6
	s_ashr_i32 s13, s12, 31
	s_lshl_b64 s[18:19], s[12:13], 20
	s_add_u32 s18, s24, s18
	s_addc_u32 s19, s25, s19
	s_and_b64 s[22:23], s[4:5], exec
	s_cselect_b32 s13, s19, s21
	s_cselect_b32 s41, s18, s20
	s_add_u32 s6, s6, 0x80080
	s_addc_u32 s7, s7, 0
	s_add_u32 s42, s20, 0x100
	v_mov_b32_e32 v2, 0
	v_mov_b32_e32 v188, 0x2f000000
	s_addc_u32 s43, s21, 0
	s_mov_b32 s44, -2
	v_mov_b32_e32 v3, v2
	v_mov_b32_e32 v4, v2
	v_mov_b32_e32 v5, v2
	v_mov_b32_e32 v6, v2
	v_mov_b32_e32 v7, v2
	v_mov_b32_e32 v8, v2
	v_mov_b32_e32 v9, v2
	v_mov_b32_e32 v18, v2
	v_mov_b32_e32 v19, v2
	v_mov_b32_e32 v20, v2
	v_mov_b32_e32 v21, v2
	v_mov_b32_e32 v22, v2
	v_mov_b32_e32 v23, v2
	v_mov_b32_e32 v24, v2
	v_mov_b32_e32 v25, v2
	v_mov_b32_e32 v34, v2
	v_mov_b32_e32 v35, v2
	v_mov_b32_e32 v36, v2
	v_mov_b32_e32 v37, v2
	v_mov_b32_e32 v38, v2
	v_mov_b32_e32 v39, v2
	v_mov_b32_e32 v40, v2
	v_mov_b32_e32 v41, v2
	v_mov_b32_e32 v50, v2
	v_mov_b32_e32 v51, v2
	v_mov_b32_e32 v52, v2
	v_mov_b32_e32 v53, v2
	v_mov_b32_e32 v54, v2
	v_mov_b32_e32 v55, v2
	v_mov_b32_e32 v56, v2
	v_mov_b32_e32 v57, v2
	v_mov_b32_e32 v10, v2
	v_mov_b32_e32 v11, v2
	v_mov_b32_e32 v12, v2
	v_mov_b32_e32 v13, v2
	v_mov_b32_e32 v14, v2
	v_mov_b32_e32 v15, v2
	v_mov_b32_e32 v16, v2
	v_mov_b32_e32 v17, v2
	v_mov_b32_e32 v26, v2
	v_mov_b32_e32 v27, v2
	v_mov_b32_e32 v28, v2
	v_mov_b32_e32 v29, v2
	v_mov_b32_e32 v30, v2
	v_mov_b32_e32 v31, v2
	v_mov_b32_e32 v32, v2
	v_mov_b32_e32 v33, v2
	v_mov_b32_e32 v42, v2
	v_mov_b32_e32 v43, v2
	v_mov_b32_e32 v44, v2
	v_mov_b32_e32 v45, v2
	v_mov_b32_e32 v46, v2
	v_mov_b32_e32 v47, v2
	v_mov_b32_e32 v48, v2
	v_mov_b32_e32 v49, v2
	v_mov_b32_e32 v58, v2
	v_mov_b32_e32 v59, v2
	v_mov_b32_e32 v60, v2
	v_mov_b32_e32 v61, v2
	v_mov_b32_e32 v62, v2
	v_mov_b32_e32 v63, v2
	v_mov_b32_e32 v64, v2
	v_mov_b32_e32 v65, v2
	v_mov_b32_e32 v66, v2
	v_mov_b32_e32 v67, v2
	v_mov_b32_e32 v68, v2
	v_mov_b32_e32 v69, v2
	v_mov_b32_e32 v70, v2
	v_mov_b32_e32 v71, v2
	v_mov_b32_e32 v72, v2
	v_mov_b32_e32 v73, v2
	v_mov_b32_e32 v82, v2
	v_mov_b32_e32 v83, v2
	v_mov_b32_e32 v84, v2
	v_mov_b32_e32 v85, v2
	v_mov_b32_e32 v86, v2
	v_mov_b32_e32 v87, v2
	v_mov_b32_e32 v88, v2
	v_mov_b32_e32 v89, v2
	v_mov_b32_e32 v98, v2
	v_mov_b32_e32 v99, v2
	v_mov_b32_e32 v100, v2
	v_mov_b32_e32 v101, v2
	v_mov_b32_e32 v102, v2
	v_mov_b32_e32 v103, v2
	v_mov_b32_e32 v104, v2
	v_mov_b32_e32 v105, v2
	v_mov_b32_e32 v114, v2
	v_mov_b32_e32 v115, v2
	v_mov_b32_e32 v116, v2
	v_mov_b32_e32 v117, v2
	v_mov_b32_e32 v118, v2
	v_mov_b32_e32 v119, v2
	v_mov_b32_e32 v120, v2
	v_mov_b32_e32 v121, v2
	v_mov_b32_e32 v74, v2
	v_mov_b32_e32 v75, v2
	v_mov_b32_e32 v76, v2
	v_mov_b32_e32 v77, v2
	v_mov_b32_e32 v78, v2
	v_mov_b32_e32 v79, v2
	v_mov_b32_e32 v80, v2
	v_mov_b32_e32 v81, v2
	v_mov_b32_e32 v90, v2
	v_mov_b32_e32 v91, v2
	v_mov_b32_e32 v92, v2
	v_mov_b32_e32 v93, v2
	v_mov_b32_e32 v94, v2
	v_mov_b32_e32 v95, v2
	v_mov_b32_e32 v96, v2
	v_mov_b32_e32 v97, v2
	v_mov_b32_e32 v106, v2
	v_mov_b32_e32 v107, v2
	v_mov_b32_e32 v108, v2
	v_mov_b32_e32 v109, v2
	v_mov_b32_e32 v110, v2
	v_mov_b32_e32 v111, v2
	v_mov_b32_e32 v112, v2
	v_mov_b32_e32 v113, v2
	v_mov_b32_e32 v122, v2
	v_mov_b32_e32 v123, v2
	v_mov_b32_e32 v124, v2
	v_mov_b32_e32 v125, v2
	v_mov_b32_e32 v126, v2
	v_mov_b32_e32 v127, v2
	v_mov_b32_e32 v128, v2
	v_mov_b32_e32 v129, v2
	v_lshrrev_b32_e32 v246, 3, v212
	v_lshl_add_u32 v246, s39, 8, v246
	v_mov_b32_e32 v247, s3
	v_lshrrev_b32_e32 v247, 1, v247
	v_add_u32_e32 v246, v246, v247
	v_lshlrev_b32_e32 v246, 7, v246
	v_and_b32_e32 v247, 7, v212
	v_lshlrev_b32_e32 v247, 4, v247
	v_add_u32_e32 v246, v246, v247
	v_lshrrev_b32_e32 v247, 4, v212
	v_lshlrev_b32_e32 v247, 5, v247
	v_sub_u32_e32 v246, v246, v247
	v_ashrrev_i32_e32 v247, 31, v246
	v_lshl_add_u64 v[248:249], v[246:247], 0, v[144:145]
	global_load_dwordx4 v[230:233], v[248:249], off
	global_load_dwordx4 v[234:237], v[248:249], off offset:1024
	global_load_dwordx4 v[238:241], v[248:249], off offset:2048
	global_load_dwordx4 v[242:245], v[248:249], off offset:3072
.LBB0_496:
	s_add_u32 s20, s6, 0xfff80080
	s_addc_u32 s21, s7, -1
	s_add_i32 s62, 0, 0x10000
	s_cmp_eq_u32 s44, 28
	s_cselect_b32 s23, s15, s21
	s_cselect_b32 s22, s40, s20
	v_add_u32_e32 v150, s62, v157
	s_cselect_b32 s21, s13, s43
	s_cselect_b32 s20, s41, s42
	s_cmp_eq_u32 s44, 0
	s_cbranch_scc0 .Lmy_up_rs_skip
	v_add_f32_e32 v230, v230, v231
	v_add_f32_e32 v232, v232, v233
	v_add_f32_e32 v230, v230, v232
	v_add_f32_e32 v234, v234, v235
	v_add_f32_e32 v236, v236, v237
	v_add_f32_e32 v234, v234, v236
	v_add_f32_e32 v238, v238, v239
	v_add_f32_e32 v240, v240, v241
	v_add_f32_e32 v238, v238, v240
	v_add_f32_e32 v242, v242, v243
	v_add_f32_e32 v244, v244, v245
	v_add_f32_e32 v242, v242, v244
	s_nop 1
	v_add_f32_dpp v230, v230, v230 quad_perm:[1,0,3,2] row_mask:0xf bank_mask:0xf
	v_add_f32_dpp v234, v234, v234 quad_perm:[1,0,3,2] row_mask:0xf bank_mask:0xf
	v_add_f32_dpp v238, v238, v238 quad_perm:[1,0,3,2] row_mask:0xf bank_mask:0xf
	v_add_f32_dpp v242, v242, v242 quad_perm:[1,0,3,2] row_mask:0xf bank_mask:0xf
	s_nop 1
	v_add_f32_dpp v230, v230, v230 quad_perm:[2,3,0,1] row_mask:0xf bank_mask:0xf
	v_add_f32_dpp v234, v234, v234 quad_perm:[2,3,0,1] row_mask:0xf bank_mask:0xf
	v_add_f32_dpp v238, v238, v238 quad_perm:[2,3,0,1] row_mask:0xf bank_mask:0xf
	v_add_f32_dpp v242, v242, v242 quad_perm:[2,3,0,1] row_mask:0xf bank_mask:0xf
	s_nop 1
	v_add_f32_dpp v230, v230, v230 row_half_mirror row_mask:0xf bank_mask:0xf
	v_add_f32_dpp v234, v234, v234 row_half_mirror row_mask:0xf bank_mask:0xf
	v_add_f32_dpp v238, v238, v238 row_half_mirror row_mask:0xf bank_mask:0xf
	v_add_f32_dpp v242, v242, v242 row_half_mirror row_mask:0xf bank_mask:0xf
	v_fmamk_f32 v230, v230, 0x3a000000, v189
	v_fmamk_f32 v234, v234, 0x3a000000, v189
	v_fmamk_f32 v238, v238, 0x3a000000, v189
	v_fmamk_f32 v242, v242, 0x3a000000, v189
	v_rsq_f32_e32 v230, v230
	v_rsq_f32_e32 v234, v234
	v_rsq_f32_e32 v238, v238
	v_rsq_f32_e32 v242, v242
	v_lshrrev_b32_e32 v246, 3, v212
	v_mov_b32_e32 v247, s3
	v_lshrrev_b32_e32 v247, 1, v247
	v_add_u32_e32 v246, v246, v247
	v_lshlrev_b32_e32 v246, 2, v246
	v_add_u32_e32 v246, 0x20000, v246
	ds_write_b32 v246, v230
	ds_write_b32 v246, v234 offset:32
	ds_write_b32 v246, v238 offset:64
	ds_write_b32 v246, v242 offset:96
; #define PG8_STAGE(bufoff, gbase, voff) do { _Pragma("unroll") for (int _i = 0; _i < 2; ++_i) \
;         __builtin_amdgcn_global_load_lds((const unsigned*)((const char*)(gbase) + (voff)[_i]), (PG8_LAS unsigned*)(lds + (bufoff) + ldsw + _i * 8192), 16, 0, 0); } while (0)
; #define PG8_LDA(dst, b, h) do { _Pragma("unroll") for (int m = 0; m < 4; ++m) _Pragma("unroll") for (int k = 0; k < 2; ++k) dst[m][k] = *(const PG8_LAS bf16x8*)(lds + PG8_SA(b, h) + aoff + m * 2048 + k * 1024); } while (0)
; #define PG8_LDB(dst, b, h) do { _Pragma("unroll") for (int n = 0; n < 2; ++n) _Pragma("unroll") for (int k = 0; k < 2; ++k) dst[n][k] = *(const PG8_LAS bf16x8*)(lds + PG8_SB(b, h) + boff + n * 2048 + k * 1024); } while (0)
; #define PG8_MMA(ai, bj, At, Bt) do { __builtin_amdgcn_s_setprio(1); _Pragma("unroll") for (int m = 0; m < 4; ++m) _Pragma("unroll") for (int n = 0; n < 2; ++n) _Pragma("unroll") for (int k = 0; k < 2; ++k) \
;         acc[ai][bj][m][n] = __builtin_amdgcn_mfma_f32_16x16x32_bf16(Bt[n][k], At[m][k], acc[ai][bj][m][n], 0, 0, 0); __builtin_amdgcn_s_setprio(0); } while (0)
; #define PG8_WAIT_V(n) asm volatile("s_waitcnt vmcnt(" #n ")" ::: "memory")
; #define PG8_WAIT_L(n) asm volatile("s_waitcnt lgkmcnt(" #n ")" ::: "memory")
; #define PG8_BAR __builtin_amdgcn_s_barrier()
; #define PG8_SCHED __builtin_amdgcn_sched_barrier(0)
; template <class Epi, class Sched, bool ALIGN_EPI = false, bool SP2 = false>
; __device__ __forceinline__ void gemm_phase(PG8_LAS unsigned char* lds, const Gemm g, const Sched& S, const Epi& E, const int wave_s) {
;     ...
;             PG8_LDB(B0, 0, 0); PG8_LDB(B1, 0, 1); PG8_SCHED; PG8_LDA(At, 0, 0); PG8_STAGE(PG8_SA(1, 1), a1 + hstep, voffA);
;             PG8_WAIT_V(8); PG8_WAIT_L(0); PG8_BAR; PG8_MMA(0, 0, At, B0); PG8_MMA(0, 1, At, B1); PG8_BAR; PG8_SCHED;
;             PG8_LDA(At, 0, 1); PG8_STAGE(PG8_SB(0, 0), b2, voffB); PG8_STAGE(PG8_SB(0, 1), b2 + hstep, voffB); PG8_STAGE(PG8_SA(0, 0), a2, voffA);
;             PG8_WAIT_V(8); PG8_WAIT_L(0); PG8_BAR; PG8_MMA(1, 0, At, B0); PG8_MMA(1, 1, At, B1); PG8_BAR; PG8_SCHED;
.Lmy_up_rs_skip:
	s_add_i32 s74, 0, 0x14000
	ds_read_b128 v[130:133], v150
	ds_read_b128 v[134:137], v150 offset:1024
	ds_read_b128 v[158:161], v150 offset:2048
	ds_read_b128 v[170:173], v150 offset:3072
	v_add_u32_e32 v150, s74, v157
	ds_read_b128 v[174:177], v150
	ds_read_b128 v[178:181], v150 offset:1024
	ds_read_b128 v[182:185], v150 offset:2048
	ds_read_b128 v[190:193], v150 offset:3072
	v_lshl_add_u64 v[150:151], s[6:7], 0, v[146:147]
	s_add_i32 m0, s27, 0xc000
	ds_read_b128 v[196:199], v169
	ds_read_b128 v[200:203], v169 offset:1024
	ds_read_b128 v[204:207], v169 offset:2048
	ds_read_b128 v[208:211], v169 offset:3072
	ds_read_b128 v[214:217], v169 offset:4096
	ds_read_b128 v[218:221], v169 offset:5120
	ds_read_b128 v[222:225], v169 offset:6144
	ds_read_b128 v[226:229], v169 offset:7168
	global_load_lds_dwordx4 v[150:151], off
	v_lshl_add_u64 v[150:151], s[6:7], 0, v[148:149]
	s_add_i32 m0, s27, 0xe000
	s_nop 0
	global_load_lds_dwordx4 v[150:151], off
	s_waitcnt vmcnt(8)
	s_waitcnt lgkmcnt(0)
	s_barrier
	s_setprio 1
	s_waitcnt lgkmcnt(0)
	v_mfma_f32_16x16x32_bf16 v[126:129], v[130:133], v[196:199], v[126:129]
	v_mfma_f32_16x16x32_bf16 v[122:125], v[158:161], v[196:199], v[122:125]
	v_mfma_f32_16x16x32_bf16 v[110:113], v[130:133], v[204:207], v[110:113]
	v_mfma_f32_16x16x32_bf16 v[106:109], v[158:161], v[204:207], v[106:109]
	v_mfma_f32_16x16x32_bf16 v[94:97], v[130:133], v[214:217], v[94:97]
	v_mfma_f32_16x16x32_bf16 v[90:93], v[158:161], v[214:217], v[90:93]
	v_mfma_f32_16x16x32_bf16 v[78:81], v[130:133], v[222:225], v[78:81]
	v_mfma_f32_16x16x32_bf16 v[74:77], v[158:161], v[222:225], v[74:77]
	v_mfma_f32_16x16x32_bf16 v[126:129], v[134:137], v[200:203], v[126:129]
	v_mfma_f32_16x16x32_bf16 v[122:125], v[170:173], v[200:203], v[122:125]
	v_mfma_f32_16x16x32_bf16 v[110:113], v[134:137], v[208:211], v[110:113]
	v_mfma_f32_16x16x32_bf16 v[106:109], v[170:173], v[208:211], v[106:109]
	v_mfma_f32_16x16x32_bf16 v[94:97], v[134:137], v[218:221], v[94:97]
	v_mfma_f32_16x16x32_bf16 v[90:93], v[170:173], v[218:221], v[90:93]
	v_mfma_f32_16x16x32_bf16 v[78:81], v[134:137], v[226:229], v[78:81]
	v_mfma_f32_16x16x32_bf16 v[74:77], v[170:173], v[226:229], v[74:77]
	s_setprio 0
	s_setprio 1
	v_mfma_f32_16x16x32_bf16 v[118:121], v[174:177], v[196:199], v[118:121]
	v_mfma_f32_16x16x32_bf16 v[114:117], v[182:185], v[196:199], v[114:117]
	v_mfma_f32_16x16x32_bf16 v[102:105], v[174:177], v[204:207], v[102:105]
	v_mfma_f32_16x16x32_bf16 v[98:101], v[182:185], v[204:207], v[98:101]
	v_mfma_f32_16x16x32_bf16 v[86:89], v[174:177], v[214:217], v[86:89]
	v_mfma_f32_16x16x32_bf16 v[82:85], v[182:185], v[214:217], v[82:85]
	v_mfma_f32_16x16x32_bf16 v[70:73], v[174:177], v[222:225], v[70:73]
	v_mfma_f32_16x16x32_bf16 v[66:69], v[182:185], v[222:225], v[66:69]
	v_mfma_f32_16x16x32_bf16 v[118:121], v[178:181], v[200:203], v[118:121]
	v_mfma_f32_16x16x32_bf16 v[114:117], v[190:193], v[200:203], v[114:117]
	v_mfma_f32_16x16x32_bf16 v[102:105], v[178:181], v[208:211], v[102:105]
	v_mfma_f32_16x16x32_bf16 v[98:101], v[190:193], v[208:211], v[98:101]
	v_mfma_f32_16x16x32_bf16 v[86:89], v[178:181], v[218:221], v[86:89]
	v_mfma_f32_16x16x32_bf16 v[82:85], v[190:193], v[218:221], v[82:85]
	v_mfma_f32_16x16x32_bf16 v[70:73], v[178:181], v[226:229], v[70:73]
	v_mfma_f32_16x16x32_bf16 v[66:69], v[190:193], v[226:229], v[66:69]
	s_setprio 0
	s_barrier
	s_add_i32 s62, s62, s26
	v_lshl_add_u64 v[150:151], s[20:21], 0, v[0:1]
	s_mov_b32 m0, s62
	ds_read_b128 v[196:199], v169 offset:16384
	ds_read_b128 v[200:203], v169 offset:17408
	ds_read_b128 v[204:207], v169 offset:18432
	ds_read_b128 v[208:211], v169 offset:19456
	ds_read_b128 v[214:217], v169 offset:20480
	ds_read_b128 v[218:221], v169 offset:21504
	ds_read_b128 v[222:225], v169 offset:22528
	ds_read_b128 v[226:229], v169 offset:23552
	global_load_lds_dwordx4 v[150:151], off
	s_add_i32 m0, s62, 0x2000
	s_add_u32 s62, s20, 0x80000
	v_lshl_add_u64 v[154:155], s[20:21], 0, v[138:139]
	s_addc_u32 s63, s21, 0
	s_add_i32 s74, s74, s26
	global_load_lds_dwordx4 v[154:155], off
	v_lshl_add_u64 v[162:163], s[62:63], 0, v[0:1]
	s_mov_b32 m0, s74
	v_lshl_add_u64 v[166:167], s[22:23], 0, v[140:141]
	global_load_lds_dwordx4 v[162:163], off
	v_lshl_add_u64 v[162:163], s[62:63], 0, v[138:139]
	s_add_i32 m0, s74, 0x2000
	s_nop 0
	global_load_lds_dwordx4 v[162:163], off
	v_lshl_add_u64 v[162:163], s[22:23], 0, v[142:143]
	s_mov_b32 m0, s27
	s_nop 0
	global_load_lds_dwordx4 v[162:163], off
	s_mov_b32 m0, s28
	s_nop 0
	global_load_lds_dwordx4 v[166:167], off
	s_waitcnt vmcnt(8)
	s_waitcnt lgkmcnt(0)
	s_barrier
; #define PG8_STAGE(bufoff, gbase, voff) do { _Pragma("unroll") for (int _i = 0; _i < 2; ++_i) \
;         __builtin_amdgcn_global_load_lds((const unsigned*)((const char*)(gbase) + (voff)[_i]), (PG8_LAS unsigned*)(lds + (bufoff) + ldsw + _i * 8192), 16, 0, 0); } while (0)
; #define PG8_LDA(dst, b, h) do { _Pragma("unroll") for (int m = 0; m < 4; ++m) _Pragma("unroll") for (int k = 0; k < 2; ++k) dst[m][k] = *(const PG8_LAS bf16x8*)(lds + PG8_SA(b, h) + aoff + m * 2048 + k * 1024); } while (0)
; #define PG8_LDB(dst, b, h) do { _Pragma("unroll") for (int n = 0; n < 2; ++n) _Pragma("unroll") for (int k = 0; k < 2; ++k) dst[n][k] = *(const PG8_LAS bf16x8*)(lds + PG8_SB(b, h) + boff + n * 2048 + k * 1024); } while (0)
; #define PG8_MMA(ai, bj, At, Bt) do { __builtin_amdgcn_s_setprio(1); _Pragma("unroll") for (int m = 0; m < 4; ++m) _Pragma("unroll") for (int n = 0; n < 2; ++n) _Pragma("unroll") for (int k = 0; k < 2; ++k) \
;         acc[ai][bj][m][n] = __builtin_amdgcn_mfma_f32_16x16x32_bf16(Bt[n][k], At[m][k], acc[ai][bj][m][n], 0, 0, 0); __builtin_amdgcn_s_setprio(0); } while (0)
; #define PG8_WAIT_V(n) asm volatile("s_waitcnt vmcnt(" #n ")" ::: "memory")
; #define PG8_WAIT_L(n) asm volatile("s_waitcnt lgkmcnt(" #n ")" ::: "memory")
; #define PG8_BAR __builtin_amdgcn_s_barrier()
; #define PG8_SCHED __builtin_amdgcn_sched_barrier(0)
; template <class Epi, class Sched, bool ALIGN_EPI = false, bool SP2 = false>
; __device__ __forceinline__ void gemm_phase(PG8_LAS unsigned char* lds, const Gemm g, const Sched& S, const Epi& E, const int wave_s) {
;     ...
;             PG8_WAIT_V(8); PG8_WAIT_L(0); PG8_BAR; PG8_MMA(1, 0, At, B0); PG8_MMA(1, 1, At, B1); PG8_BAR; PG8_SCHED;
;             PG8_LDB(B0, 1, 0); PG8_LDB(B1, 1, 1); PG8_SCHED; PG8_LDA(At, 1, 0); PG8_STAGE(PG8_SA(0, 1), a2 + hstep, voffA);
;             PG8_WAIT_V(8); PG8_WAIT_L(0); PG8_BAR; PG8_MMA(0, 0, At, B0); PG8_MMA(0, 1, At, B1); PG8_BAR; PG8_SCHED;
	s_setprio 1
	s_waitcnt lgkmcnt(0)
	v_mfma_f32_16x16x32_bf16 v[62:65], v[130:133], v[196:199], v[62:65]
	v_mfma_f32_16x16x32_bf16 v[58:61], v[158:161], v[196:199], v[58:61]
	v_mfma_f32_16x16x32_bf16 v[46:49], v[130:133], v[204:207], v[46:49]
	v_mfma_f32_16x16x32_bf16 v[42:45], v[158:161], v[204:207], v[42:45]
	v_mfma_f32_16x16x32_bf16 v[30:33], v[130:133], v[214:217], v[30:33]
	v_mfma_f32_16x16x32_bf16 v[26:29], v[158:161], v[214:217], v[26:29]
	v_mfma_f32_16x16x32_bf16 v[14:17], v[130:133], v[222:225], v[14:17]
	v_mfma_f32_16x16x32_bf16 v[10:13], v[158:161], v[222:225], v[10:13]
	v_mfma_f32_16x16x32_bf16 v[62:65], v[134:137], v[200:203], v[62:65]
	v_mfma_f32_16x16x32_bf16 v[58:61], v[170:173], v[200:203], v[58:61]
	v_mfma_f32_16x16x32_bf16 v[46:49], v[134:137], v[208:211], v[46:49]
	v_mfma_f32_16x16x32_bf16 v[42:45], v[170:173], v[208:211], v[42:45]
	v_mfma_f32_16x16x32_bf16 v[30:33], v[134:137], v[218:221], v[30:33]
	v_mfma_f32_16x16x32_bf16 v[26:29], v[170:173], v[218:221], v[26:29]
	v_mfma_f32_16x16x32_bf16 v[14:17], v[134:137], v[226:229], v[14:17]
	v_mfma_f32_16x16x32_bf16 v[10:13], v[170:173], v[226:229], v[10:13]
	s_setprio 0
	s_setprio 1
	v_mfma_f32_16x16x32_bf16 v[54:57], v[174:177], v[196:199], v[54:57]
	v_mfma_f32_16x16x32_bf16 v[50:53], v[182:185], v[196:199], v[50:53]
	v_mfma_f32_16x16x32_bf16 v[38:41], v[174:177], v[204:207], v[38:41]
	v_mfma_f32_16x16x32_bf16 v[34:37], v[182:185], v[204:207], v[34:37]
	v_mfma_f32_16x16x32_bf16 v[22:25], v[174:177], v[214:217], v[22:25]
	v_mfma_f32_16x16x32_bf16 v[18:21], v[182:185], v[214:217], v[18:21]
	v_mfma_f32_16x16x32_bf16 v[6:9], v[174:177], v[222:225], v[6:9]
	v_mfma_f32_16x16x32_bf16 v[2:5], v[182:185], v[222:225], v[2:5]
	v_mfma_f32_16x16x32_bf16 v[54:57], v[178:181], v[200:203], v[54:57]
	v_mfma_f32_16x16x32_bf16 v[50:53], v[190:193], v[200:203], v[50:53]
	v_mfma_f32_16x16x32_bf16 v[38:41], v[178:181], v[208:211], v[38:41]
	v_mfma_f32_16x16x32_bf16 v[34:37], v[190:193], v[208:211], v[34:37]
	v_mfma_f32_16x16x32_bf16 v[22:25], v[178:181], v[218:221], v[22:25]
	v_mfma_f32_16x16x32_bf16 v[18:21], v[190:193], v[218:221], v[18:21]
	v_mfma_f32_16x16x32_bf16 v[6:9], v[178:181], v[226:229], v[6:9]
	v_mfma_f32_16x16x32_bf16 v[2:5], v[190:193], v[226:229], v[2:5]
	s_setprio 0
	s_barrier
	s_add_i32 s62, 0, 0x18000
	v_add_u32_e32 v152, s62, v157
	s_add_i32 s63, 0, 0x1c000
	ds_read_b128 v[130:133], v152
	ds_read_b128 v[134:137], v152 offset:1024
	ds_read_b128 v[158:161], v152 offset:2048
	ds_read_b128 v[170:173], v152 offset:3072
	v_add_u32_e32 v152, s63, v157
	ds_read_b128 v[174:177], v152
	ds_read_b128 v[178:181], v152 offset:1024
	ds_read_b128 v[182:185], v152 offset:2048
	ds_read_b128 v[190:193], v152 offset:3072
	s_add_u32 s22, s22, 0x80000
	s_addc_u32 s23, s23, 0
	s_mov_b32 m0, s29
	v_lshl_add_u64 v[186:187], s[22:23], 0, v[142:143]
	ds_read_b128 v[196:199], v169 offset:32768
	ds_read_b128 v[200:203], v169 offset:33792
	ds_read_b128 v[204:207], v169 offset:34816
	ds_read_b128 v[208:211], v169 offset:35840
	ds_read_b128 v[214:217], v169 offset:36864
	ds_read_b128 v[218:221], v169 offset:37888
	ds_read_b128 v[222:225], v169 offset:38912
	ds_read_b128 v[226:229], v169 offset:39936
	global_load_lds_dwordx4 v[186:187], off
	v_lshl_add_u64 v[186:187], s[22:23], 0, v[140:141]
	s_mov_b32 m0, s30
	s_nop 0
	global_load_lds_dwordx4 v[186:187], off
	s_waitcnt vmcnt(8)
	s_waitcnt lgkmcnt(0)
	s_barrier
	s_setprio 1
	s_waitcnt lgkmcnt(0)
	v_mfma_f32_16x16x32_bf16 v[126:129], v[130:133], v[196:199], v[126:129]
	v_mfma_f32_16x16x32_bf16 v[122:125], v[158:161], v[196:199], v[122:125]
	v_mfma_f32_16x16x32_bf16 v[110:113], v[130:133], v[204:207], v[110:113]
	v_mfma_f32_16x16x32_bf16 v[106:109], v[158:161], v[204:207], v[106:109]
	v_mfma_f32_16x16x32_bf16 v[94:97], v[130:133], v[214:217], v[94:97]
	v_mfma_f32_16x16x32_bf16 v[90:93], v[158:161], v[214:217], v[90:93]
	v_mfma_f32_16x16x32_bf16 v[78:81], v[130:133], v[222:225], v[78:81]
	v_mfma_f32_16x16x32_bf16 v[74:77], v[158:161], v[222:225], v[74:77]
	v_mfma_f32_16x16x32_bf16 v[126:129], v[134:137], v[200:203], v[126:129]
	v_mfma_f32_16x16x32_bf16 v[122:125], v[170:173], v[200:203], v[122:125]
	v_mfma_f32_16x16x32_bf16 v[110:113], v[134:137], v[208:211], v[110:113]
	v_mfma_f32_16x16x32_bf16 v[106:109], v[170:173], v[208:211], v[106:109]
	v_mfma_f32_16x16x32_bf16 v[94:97], v[134:137], v[218:221], v[94:97]
	v_mfma_f32_16x16x32_bf16 v[90:93], v[170:173], v[218:221], v[90:93]
	v_mfma_f32_16x16x32_bf16 v[78:81], v[134:137], v[226:229], v[78:81]
	v_mfma_f32_16x16x32_bf16 v[74:77], v[170:173], v[226:229], v[74:77]
	s_setprio 0
	s_setprio 1
	v_mfma_f32_16x16x32_bf16 v[118:121], v[174:177], v[196:199], v[118:121]
	v_mfma_f32_16x16x32_bf16 v[114:117], v[182:185], v[196:199], v[114:117]
	v_mfma_f32_16x16x32_bf16 v[102:105], v[174:177], v[204:207], v[102:105]
	v_mfma_f32_16x16x32_bf16 v[98:101], v[182:185], v[204:207], v[98:101]
	v_mfma_f32_16x16x32_bf16 v[86:89], v[174:177], v[214:217], v[86:89]
	v_mfma_f32_16x16x32_bf16 v[82:85], v[182:185], v[214:217], v[82:85]
	v_mfma_f32_16x16x32_bf16 v[70:73], v[174:177], v[222:225], v[70:73]
	v_mfma_f32_16x16x32_bf16 v[66:69], v[182:185], v[222:225], v[66:69]
	v_mfma_f32_16x16x32_bf16 v[118:121], v[178:181], v[200:203], v[118:121]
	v_mfma_f32_16x16x32_bf16 v[114:117], v[190:193], v[200:203], v[114:117]
	v_mfma_f32_16x16x32_bf16 v[102:105], v[178:181], v[208:211], v[102:105]
	v_mfma_f32_16x16x32_bf16 v[98:101], v[190:193], v[208:211], v[98:101]
	v_mfma_f32_16x16x32_bf16 v[86:89], v[178:181], v[218:221], v[86:89]
	v_mfma_f32_16x16x32_bf16 v[82:85], v[190:193], v[218:221], v[82:85]
	v_mfma_f32_16x16x32_bf16 v[70:73], v[178:181], v[226:229], v[70:73]
	v_mfma_f32_16x16x32_bf16 v[66:69], v[190:193], v[226:229], v[66:69]
	s_setprio 0
	s_barrier
; __device__ __forceinline__ unsigned cvt_pk_bf16(float lo, float hi) { f32x2 v = {lo, hi}; bf16x2_t b = __builtin_convertvector(v, bf16x2_t); return __builtin_bit_cast(unsigned, b); }
; #define PG8_STAGE(bufoff, gbase, voff) do { _Pragma("unroll") for (int _i = 0; _i < 2; ++_i) \
;         __builtin_amdgcn_global_load_lds((const unsigned*)((const char*)(gbase) + (voff)[_i]), (PG8_LAS unsigned*)(lds + (bufoff) + ldsw + _i * 8192), 16, 0, 0); } while (0)
; #define PG8_LDA(dst, b, h) do { _Pragma("unroll") for (int m = 0; m < 4; ++m) _Pragma("unroll") for (int k = 0; k < 2; ++k) dst[m][k] = *(const PG8_LAS bf16x8*)(lds + PG8_SA(b, h) + aoff + m * 2048 + k * 1024); } while (0)
; #define PG8_BAR __builtin_amdgcn_s_barrier()
;     __device__ __forceinline__ void operator()(const f32x4 (&acc)[2][2][4][2], const Unit& u, int wr, int wc, int fr, int fq) const {
;         const int row0 = u.pm * BM + wr * 64 + fr, col0 = u.pn * BM + wc * 32 + 8 * fq;
;         float rs[2][4];
; #pragma unroll
;         for (int ai = 0; ai < 2; ++ai)
; #pragma unroll
;             for (int m = 0; m < 4; ++m) rs[ai][m] = row_rstd(rowss, row0 + ai * HALF + m * 16, fq);
; #pragma unroll
;         for (int ai = 0; ai < 2; ++ai)
; #pragma unroll
;             for (int m = 0; m < 4; ++m) { bf16_t* rowp = O + (size_t)(row0 + ai * HALF + m * 16) * ldc + col0; const float r_ = rs[ai][m];
; #pragma unroll
;                 for (int bj = 0; bj < 2; ++bj) { f32x4 v0 = acc[ai][bj][m][0] * r_, v1 = acc[ai][bj][m][1] * r_;
; #pragma unroll
;                     for (int e = 0; e < 4; ++e) { const float a = fmaxf(v0[e], 0.f), b = fmaxf(v1[e], 0.f); v0[e] = a * a; v1[e] = b * b; }
;                     u32x4 w; w.x = cvt_pk_bf16(v0[0], v0[1]); w.y = cvt_pk_bf16(v0[2], v0[3]); w.z = cvt_pk_bf16(v1[0], v1[1]); w.w = cvt_pk_bf16(v1[2], v1[3]);
;                     *(u32x4*)(rowp + bj * HALF) = w; } }
; template <class Epi, class Sched, bool ALIGN_EPI = false, bool SP2 = false>
; __device__ __forceinline__ void gemm_phase(PG8_LAS unsigned char* lds, const Gemm g, const Sched& S, const Epi& E, const int wave_s) {
;     ...
;             PG8_LDA(At, 1, 1); PG8_STAGE(PG8_SB(1, 0), b3, voffB); PG8_STAGE(PG8_SB(1, 1), b3 + hstep, voffB); PG8_STAGE(PG8_SA(1, 0), a3, voffA);
;             PG8_WAIT_V(8); PG8_WAIT_L(0); PG8_BAR; PG8_MMA(1, 0, At, B0); PG8_MMA(1, 1, At, B1); PG8_BAR; PG8_SCHED;
	s_add_i32 s22, s62, s26
	v_lshl_add_u64 v[150:151], v[150:151], 0, s[92:93]
	s_mov_b32 m0, s22
	ds_read_b128 v[196:199], v169 offset:49152
	ds_read_b128 v[200:203], v169 offset:50176
	ds_read_b128 v[204:207], v169 offset:51200
	ds_read_b128 v[208:211], v169 offset:52224
	ds_read_b128 v[214:217], v169 offset:53248
	ds_read_b128 v[218:221], v169 offset:54272
	ds_read_b128 v[222:225], v169 offset:55296
	ds_read_b128 v[226:229], v169 offset:56320
	global_load_lds_dwordx4 v[150:151], off
	s_add_i32 m0, s22, 0x2000
	s_add_u32 s20, s20, 0x80080
	v_lshl_add_u64 v[150:151], v[154:155], 0, s[92:93]
	s_addc_u32 s21, s21, 0
	s_add_i32 s22, s63, s26
	global_load_lds_dwordx4 v[150:151], off
	v_lshl_add_u64 v[150:151], s[20:21], 0, v[0:1]
	s_mov_b32 m0, s22
	s_nop 0
	global_load_lds_dwordx4 v[150:151], off
	v_lshl_add_u64 v[150:151], s[20:21], 0, v[138:139]
	s_add_i32 m0, s22, 0x2000
	s_nop 0
	global_load_lds_dwordx4 v[150:151], off
	v_lshl_add_u64 v[150:151], v[162:163], 0, s[92:93]
	s_mov_b32 m0, s31
	s_nop 0
	global_load_lds_dwordx4 v[150:151], off
	v_lshl_add_u64 v[150:151], v[166:167], 0, s[92:93]
	s_mov_b32 m0, s34
	s_nop 0
	global_load_lds_dwordx4 v[150:151], off
	s_waitcnt vmcnt(8)
	s_waitcnt lgkmcnt(0)
	s_barrier
	s_setprio 1
	s_waitcnt lgkmcnt(0)
	v_mfma_f32_16x16x32_bf16 v[62:65], v[130:133], v[196:199], v[62:65]
	v_mfma_f32_16x16x32_bf16 v[58:61], v[158:161], v[196:199], v[58:61]
	v_mfma_f32_16x16x32_bf16 v[46:49], v[130:133], v[204:207], v[46:49]
	v_mfma_f32_16x16x32_bf16 v[42:45], v[158:161], v[204:207], v[42:45]
	v_mfma_f32_16x16x32_bf16 v[30:33], v[130:133], v[214:217], v[30:33]
	v_mfma_f32_16x16x32_bf16 v[26:29], v[158:161], v[214:217], v[26:29]
	v_mfma_f32_16x16x32_bf16 v[14:17], v[130:133], v[222:225], v[14:17]
	v_mfma_f32_16x16x32_bf16 v[10:13], v[158:161], v[222:225], v[10:13]
	v_mfma_f32_16x16x32_bf16 v[62:65], v[134:137], v[200:203], v[62:65]
	v_mfma_f32_16x16x32_bf16 v[58:61], v[170:173], v[200:203], v[58:61]
	v_mfma_f32_16x16x32_bf16 v[46:49], v[134:137], v[208:211], v[46:49]
	v_mfma_f32_16x16x32_bf16 v[42:45], v[170:173], v[208:211], v[42:45]
	v_mfma_f32_16x16x32_bf16 v[30:33], v[134:137], v[218:221], v[30:33]
	v_mfma_f32_16x16x32_bf16 v[26:29], v[170:173], v[218:221], v[26:29]
	v_mfma_f32_16x16x32_bf16 v[14:17], v[134:137], v[226:229], v[14:17]
	v_mfma_f32_16x16x32_bf16 v[10:13], v[170:173], v[226:229], v[10:13]
	s_setprio 0
	s_setprio 1
	v_mfma_f32_16x16x32_bf16 v[54:57], v[174:177], v[196:199], v[54:57]
	v_mfma_f32_16x16x32_bf16 v[50:53], v[182:185], v[196:199], v[50:53]
	v_mfma_f32_16x16x32_bf16 v[38:41], v[174:177], v[204:207], v[38:41]
	v_mfma_f32_16x16x32_bf16 v[34:37], v[182:185], v[204:207], v[34:37]
	v_mfma_f32_16x16x32_bf16 v[22:25], v[174:177], v[214:217], v[22:25]
	v_mfma_f32_16x16x32_bf16 v[18:21], v[182:185], v[214:217], v[18:21]
	v_mfma_f32_16x16x32_bf16 v[6:9], v[174:177], v[222:225], v[6:9]
	v_mfma_f32_16x16x32_bf16 v[2:5], v[182:185], v[222:225], v[2:5]
	v_mfma_f32_16x16x32_bf16 v[54:57], v[178:181], v[200:203], v[54:57]
	v_mfma_f32_16x16x32_bf16 v[50:53], v[190:193], v[200:203], v[50:53]
	v_mfma_f32_16x16x32_bf16 v[38:41], v[178:181], v[208:211], v[38:41]
	v_mfma_f32_16x16x32_bf16 v[34:37], v[190:193], v[208:211], v[34:37]
	v_mfma_f32_16x16x32_bf16 v[22:25], v[178:181], v[218:221], v[22:25]
	v_mfma_f32_16x16x32_bf16 v[18:21], v[190:193], v[218:221], v[18:21]
	v_mfma_f32_16x16x32_bf16 v[6:9], v[178:181], v[226:229], v[6:9]
	v_mfma_f32_16x16x32_bf16 v[2:5], v[190:193], v[226:229], v[2:5]
	s_setprio 0
	s_barrier
	s_add_i32 s44, s44, 2
	s_add_u32 s6, s6, 0x100
	s_addc_u32 s7, s7, 0
	s_add_u32 s42, s42, 0x100
	s_addc_u32 s43, s43, 0
	s_cmp_gt_u32 s44, 29
	s_cbranch_scc0 .LBB0_496
	s_and_b64 vcc, exec, s[10:11]
	s_cbranch_vccz .LBB0_499
	s_barrier
.LBB0_499:
	v_lshlrev_b32_e32 v204, 2, v153
	v_add_u32_e32 v204, 0x20000, v204
	ds_read2_b32 v[196:197], v204 offset0:0 offset1:16
	ds_read2_b32 v[198:199], v204 offset0:32 offset1:48
	ds_read2_b32 v[200:201], v204 offset0:128 offset1:144
	ds_read2_b32 v[202:203], v204 offset0:160 offset1:176
	v_lshl_add_u32 v205, s39, 8, v153
	v_lshl_or_b32 v206, s38, 8, v165
	v_lshlrev_b32_e32 v206, 1, v206
	v_lshl_add_u32 v205, v205, 14, v206
	s_waitcnt lgkmcnt(0)
	v_mul_f32_e32 v126, v126, v196
	v_mul_f32_e32 v127, v127, v196
	v_mul_f32_e32 v128, v128, v196
	v_mul_f32_e32 v129, v129, v196
	v_mul_f32_e32 v122, v122, v196
	v_mul_f32_e32 v123, v123, v196
	v_mul_f32_e32 v124, v124, v196
	v_mul_f32_e32 v125, v125, v196
	v_max_f32_e32 v126, 0, v126
	v_max_f32_e32 v127, 0, v127
	v_max_f32_e32 v128, 0, v128
	v_max_f32_e32 v129, 0, v129
	v_max_f32_e32 v122, 0, v122
	v_max_f32_e32 v123, 0, v123
	v_max_f32_e32 v124, 0, v124
	v_max_f32_e32 v125, 0, v125
	v_pk_mul_f32 v[126:127], v[126:127], v[126:127]
	v_pk_mul_f32 v[128:129], v[128:129], v[128:129]
	v_pk_mul_f32 v[122:123], v[122:123], v[122:123]
	v_pk_mul_f32 v[124:125], v[124:125], v[124:125]
	v_cvt_pk_bf16_f32 v126, v126, v127
	v_cvt_pk_bf16_f32 v127, v128, v129
	v_cvt_pk_bf16_f32 v128, v122, v123
	v_cvt_pk_bf16_f32 v129, v124, v125
	global_store_dwordx4 v205, v[126:129], s[94:95]
	v_mul_f32_e32 v118, v118, v196
	v_mul_f32_e32 v119, v119, v196
	v_mul_f32_e32 v120, v120, v196
	v_mul_f32_e32 v121, v121, v196
	v_mul_f32_e32 v114, v114, v196
	v_mul_f32_e32 v115, v115, v196
	v_mul_f32_e32 v116, v116, v196
	v_mul_f32_e32 v117, v117, v196
	v_max_f32_e32 v118, 0, v118
	v_max_f32_e32 v119, 0, v119
	v_max_f32_e32 v120, 0, v120
	v_max_f32_e32 v121, 0, v121
	v_max_f32_e32 v114, 0, v114
	v_max_f32_e32 v115, 0, v115
	v_max_f32_e32 v116, 0, v116
	v_max_f32_e32 v117, 0, v117
	v_pk_mul_f32 v[118:119], v[118:119], v[118:119]
	v_pk_mul_f32 v[120:121], v[120:121], v[120:121]
; __device__ __forceinline__ unsigned cvt_pk_bf16(float lo, float hi) { f32x2 v = {lo, hi}; bf16x2_t b = __builtin_convertvector(v, bf16x2_t); return __builtin_bit_cast(unsigned, b); }
;     __device__ __forceinline__ void operator()(const f32x4 (&acc)[2][2][4][2], const Unit& u, int wr, int wc, int fr, int fq) const {
;     ...
;             for (int m = 0; m < 4; ++m) { bf16_t* rowp = O + (size_t)(row0 + ai * HALF + m * 16) * ldc + col0; const float r_ = rs[ai][m];
; #pragma unroll
;                 for (int bj = 0; bj < 2; ++bj) { f32x4 v0 = acc[ai][bj][m][0] * r_, v1 = acc[ai][bj][m][1] * r_;
; #pragma unroll
;                     for (int e = 0; e < 4; ++e) { const float a = fmaxf(v0[e], 0.f), b = fmaxf(v1[e], 0.f); v0[e] = a * a; v1[e] = b * b; }
;                     u32x4 w; w.x = cvt_pk_bf16(v0[0], v0[1]); w.y = cvt_pk_bf16(v0[2], v0[3]); w.z = cvt_pk_bf16(v1[0], v1[1]); w.w = cvt_pk_bf16(v1[2], v1[3]);
;                     *(u32x4*)(rowp + bj * HALF) = w; } }
	v_pk_mul_f32 v[114:115], v[114:115], v[114:115]
	v_pk_mul_f32 v[116:117], v[116:117], v[116:117]
	v_cvt_pk_bf16_f32 v118, v118, v119
	v_cvt_pk_bf16_f32 v119, v120, v121
	v_cvt_pk_bf16_f32 v120, v114, v115
	v_cvt_pk_bf16_f32 v121, v116, v117
	global_store_dwordx4 v205, v[118:121], s[94:95] offset:256
	v_add_u32_e32 v207, 0x40000, v205
	v_mul_f32_e32 v110, v110, v197
	v_mul_f32_e32 v111, v111, v197
	v_mul_f32_e32 v112, v112, v197
	v_mul_f32_e32 v113, v113, v197
	v_mul_f32_e32 v106, v106, v197
	v_mul_f32_e32 v107, v107, v197
	v_mul_f32_e32 v108, v108, v197
	v_mul_f32_e32 v109, v109, v197
	v_max_f32_e32 v110, 0, v110
	v_max_f32_e32 v111, 0, v111
	v_max_f32_e32 v112, 0, v112
	v_max_f32_e32 v113, 0, v113
	v_max_f32_e32 v106, 0, v106
	v_max_f32_e32 v107, 0, v107
	v_max_f32_e32 v108, 0, v108
	v_max_f32_e32 v109, 0, v109
	v_pk_mul_f32 v[110:111], v[110:111], v[110:111]
	v_pk_mul_f32 v[112:113], v[112:113], v[112:113]
	v_pk_mul_f32 v[106:107], v[106:107], v[106:107]
	v_pk_mul_f32 v[108:109], v[108:109], v[108:109]
	v_cvt_pk_bf16_f32 v110, v110, v111
	v_cvt_pk_bf16_f32 v111, v112, v113
	v_cvt_pk_bf16_f32 v112, v106, v107
	v_cvt_pk_bf16_f32 v113, v108, v109
	global_store_dwordx4 v207, v[110:113], s[94:95]
	v_mul_f32_e32 v102, v102, v197
	v_mul_f32_e32 v103, v103, v197
	v_mul_f32_e32 v104, v104, v197
	v_mul_f32_e32 v105, v105, v197
	v_mul_f32_e32 v98, v98, v197
	v_mul_f32_e32 v99, v99, v197
	v_mul_f32_e32 v100, v100, v197
	v_mul_f32_e32 v101, v101, v197
	v_max_f32_e32 v102, 0, v102
	v_max_f32_e32 v103, 0, v103
	v_max_f32_e32 v104, 0, v104
	v_max_f32_e32 v105, 0, v105
	v_max_f32_e32 v98, 0, v98
	v_max_f32_e32 v99, 0, v99
	v_max_f32_e32 v100, 0, v100
	v_max_f32_e32 v101, 0, v101
	v_pk_mul_f32 v[102:103], v[102:103], v[102:103]
	v_pk_mul_f32 v[104:105], v[104:105], v[104:105]
	v_pk_mul_f32 v[98:99], v[98:99], v[98:99]
	v_pk_mul_f32 v[100:101], v[100:101], v[100:101]
	v_cvt_pk_bf16_f32 v102, v102, v103
	v_cvt_pk_bf16_f32 v103, v104, v105
	v_cvt_pk_bf16_f32 v104, v98, v99
	v_cvt_pk_bf16_f32 v105, v100, v101
	global_store_dwordx4 v207, v[102:105], s[94:95] offset:256
	v_add_u32_e32 v207, 0x80000, v205
	v_mul_f32_e32 v94, v94, v198
	v_mul_f32_e32 v95, v95, v198
	v_mul_f32_e32 v96, v96, v198
	v_mul_f32_e32 v97, v97, v198
	v_mul_f32_e32 v90, v90, v198
	v_mul_f32_e32 v91, v91, v198
	v_mul_f32_e32 v92, v92, v198
	v_mul_f32_e32 v93, v93, v198
	v_max_f32_e32 v94, 0, v94
	v_max_f32_e32 v95, 0, v95
	v_max_f32_e32 v96, 0, v96
	v_max_f32_e32 v97, 0, v97
	v_max_f32_e32 v90, 0, v90
	v_max_f32_e32 v91, 0, v91
	v_max_f32_e32 v92, 0, v92
	v_max_f32_e32 v93, 0, v93
	v_pk_mul_f32 v[94:95], v[94:95], v[94:95]
	v_pk_mul_f32 v[96:97], v[96:97], v[96:97]
	v_pk_mul_f32 v[90:91], v[90:91], v[90:91]
	v_pk_mul_f32 v[92:93], v[92:93], v[92:93]
	v_cvt_pk_bf16_f32 v94, v94, v95
	v_cvt_pk_bf16_f32 v95, v96, v97
	v_cvt_pk_bf16_f32 v96, v90, v91
	v_cvt_pk_bf16_f32 v97, v92, v93
	global_store_dwordx4 v207, v[94:97], s[94:95]
	v_mul_f32_e32 v86, v86, v198
	v_mul_f32_e32 v87, v87, v198
	v_mul_f32_e32 v88, v88, v198
	v_mul_f32_e32 v89, v89, v198
	v_mul_f32_e32 v82, v82, v198
	v_mul_f32_e32 v83, v83, v198
	v_mul_f32_e32 v84, v84, v198
	v_mul_f32_e32 v85, v85, v198
	v_max_f32_e32 v86, 0, v86
	v_max_f32_e32 v87, 0, v87
	v_max_f32_e32 v88, 0, v88
	v_max_f32_e32 v89, 0, v89
	v_max_f32_e32 v82, 0, v82
	v_max_f32_e32 v83, 0, v83
	v_max_f32_e32 v84, 0, v84
	v_max_f32_e32 v85, 0, v85
	v_pk_mul_f32 v[86:87], v[86:87], v[86:87]
	v_pk_mul_f32 v[88:89], v[88:89], v[88:89]
	v_pk_mul_f32 v[82:83], v[82:83], v[82:83]
	v_pk_mul_f32 v[84:85], v[84:85], v[84:85]
	v_cvt_pk_bf16_f32 v86, v86, v87
	v_cvt_pk_bf16_f32 v87, v88, v89
	v_cvt_pk_bf16_f32 v88, v82, v83
	v_cvt_pk_bf16_f32 v89, v84, v85
	global_store_dwordx4 v207, v[86:89], s[94:95] offset:256
	v_add_u32_e32 v207, 0xc0000, v205
	v_mul_f32_e32 v78, v78, v199
	v_mul_f32_e32 v79, v79, v199
	v_mul_f32_e32 v80, v80, v199
	v_mul_f32_e32 v81, v81, v199
	v_mul_f32_e32 v74, v74, v199
	v_mul_f32_e32 v75, v75, v199
	v_mul_f32_e32 v76, v76, v199
	v_mul_f32_e32 v77, v77, v199
	v_max_f32_e32 v78, 0, v78
	v_max_f32_e32 v79, 0, v79
	v_max_f32_e32 v80, 0, v80
	v_max_f32_e32 v81, 0, v81
	v_max_f32_e32 v74, 0, v74
	v_max_f32_e32 v75, 0, v75
	v_max_f32_e32 v76, 0, v76
	v_max_f32_e32 v77, 0, v77
	v_pk_mul_f32 v[78:79], v[78:79], v[78:79]
	v_pk_mul_f32 v[80:81], v[80:81], v[80:81]
	v_pk_mul_f32 v[74:75], v[74:75], v[74:75]
	v_pk_mul_f32 v[76:77], v[76:77], v[76:77]
	v_cvt_pk_bf16_f32 v78, v78, v79
	v_cvt_pk_bf16_f32 v79, v80, v81
	v_cvt_pk_bf16_f32 v80, v74, v75
	v_cvt_pk_bf16_f32 v81, v76, v77
	global_store_dwordx4 v207, v[78:81], s[94:95]
	v_mul_f32_e32 v70, v70, v199
	v_mul_f32_e32 v71, v71, v199
	v_mul_f32_e32 v72, v72, v199
	v_mul_f32_e32 v73, v73, v199
	v_mul_f32_e32 v66, v66, v199
	v_mul_f32_e32 v67, v67, v199
	v_mul_f32_e32 v68, v68, v199
	v_mul_f32_e32 v69, v69, v199
	v_max_f32_e32 v70, 0, v70
	v_max_f32_e32 v71, 0, v71
	v_max_f32_e32 v72, 0, v72
	v_max_f32_e32 v73, 0, v73
	v_max_f32_e32 v66, 0, v66
	v_max_f32_e32 v67, 0, v67
	v_max_f32_e32 v68, 0, v68
	v_max_f32_e32 v69, 0, v69
	v_pk_mul_f32 v[70:71], v[70:71], v[70:71]
	v_pk_mul_f32 v[72:73], v[72:73], v[72:73]
	v_pk_mul_f32 v[66:67], v[66:67], v[66:67]
	v_pk_mul_f32 v[68:69], v[68:69], v[68:69]
	v_cvt_pk_bf16_f32 v70, v70, v71
	v_cvt_pk_bf16_f32 v71, v72, v73
	v_cvt_pk_bf16_f32 v72, v66, v67
	v_cvt_pk_bf16_f32 v73, v68, v69
	global_store_dwordx4 v207, v[70:73], s[94:95] offset:256
	v_add_u32_e32 v207, 0x200000, v205
	v_mul_f32_e32 v62, v62, v200
	v_mul_f32_e32 v63, v63, v200
	v_mul_f32_e32 v64, v64, v200
	v_mul_f32_e32 v65, v65, v200
	v_mul_f32_e32 v58, v58, v200
	v_mul_f32_e32 v59, v59, v200
	v_mul_f32_e32 v60, v60, v200
; __device__ __forceinline__ unsigned cvt_pk_bf16(float lo, float hi) { f32x2 v = {lo, hi}; bf16x2_t b = __builtin_convertvector(v, bf16x2_t); return __builtin_bit_cast(unsigned, b); }
;     __device__ __forceinline__ void operator()(const f32x4 (&acc)[2][2][4][2], const Unit& u, int wr, int wc, int fr, int fq) const {
;     ...
;             for (int m = 0; m < 4; ++m) { bf16_t* rowp = O + (size_t)(row0 + ai * HALF + m * 16) * ldc + col0; const float r_ = rs[ai][m];
; #pragma unroll
;                 for (int bj = 0; bj < 2; ++bj) { f32x4 v0 = acc[ai][bj][m][0] * r_, v1 = acc[ai][bj][m][1] * r_;
; #pragma unroll
;                     for (int e = 0; e < 4; ++e) { const float a = fmaxf(v0[e], 0.f), b = fmaxf(v1[e], 0.f); v0[e] = a * a; v1[e] = b * b; }
;                     u32x4 w; w.x = cvt_pk_bf16(v0[0], v0[1]); w.y = cvt_pk_bf16(v0[2], v0[3]); w.z = cvt_pk_bf16(v1[0], v1[1]); w.w = cvt_pk_bf16(v1[2], v1[3]);
;                     *(u32x4*)(rowp + bj * HALF) = w; } }
	v_mul_f32_e32 v61, v61, v200
	v_max_f32_e32 v62, 0, v62
	v_max_f32_e32 v63, 0, v63
	v_max_f32_e32 v64, 0, v64
	v_max_f32_e32 v65, 0, v65
	v_max_f32_e32 v58, 0, v58
	v_max_f32_e32 v59, 0, v59
	v_max_f32_e32 v60, 0, v60
	v_max_f32_e32 v61, 0, v61
	v_pk_mul_f32 v[62:63], v[62:63], v[62:63]
	v_pk_mul_f32 v[64:65], v[64:65], v[64:65]
	v_pk_mul_f32 v[58:59], v[58:59], v[58:59]
	v_pk_mul_f32 v[60:61], v[60:61], v[60:61]
	v_cvt_pk_bf16_f32 v62, v62, v63
	v_cvt_pk_bf16_f32 v63, v64, v65
	v_cvt_pk_bf16_f32 v64, v58, v59
	v_cvt_pk_bf16_f32 v65, v60, v61
	global_store_dwordx4 v207, v[62:65], s[94:95]
	v_mul_f32_e32 v54, v54, v200
	v_mul_f32_e32 v55, v55, v200
	v_mul_f32_e32 v56, v56, v200
	v_mul_f32_e32 v57, v57, v200
	v_mul_f32_e32 v50, v50, v200
	v_mul_f32_e32 v51, v51, v200
	v_mul_f32_e32 v52, v52, v200
	v_mul_f32_e32 v53, v53, v200
	v_max_f32_e32 v54, 0, v54
	v_max_f32_e32 v55, 0, v55
	v_max_f32_e32 v56, 0, v56
	v_max_f32_e32 v57, 0, v57
	v_max_f32_e32 v50, 0, v50
	v_max_f32_e32 v51, 0, v51
	v_max_f32_e32 v52, 0, v52
	v_max_f32_e32 v53, 0, v53
	v_pk_mul_f32 v[54:55], v[54:55], v[54:55]
	v_pk_mul_f32 v[56:57], v[56:57], v[56:57]
	v_pk_mul_f32 v[50:51], v[50:51], v[50:51]
	v_pk_mul_f32 v[52:53], v[52:53], v[52:53]
	v_cvt_pk_bf16_f32 v54, v54, v55
	v_cvt_pk_bf16_f32 v55, v56, v57
	v_cvt_pk_bf16_f32 v56, v50, v51
	v_cvt_pk_bf16_f32 v57, v52, v53
	global_store_dwordx4 v207, v[54:57], s[94:95] offset:256
	v_add_u32_e32 v207, 0x240000, v205
	v_mul_f32_e32 v46, v46, v201
	v_mul_f32_e32 v47, v47, v201
	v_mul_f32_e32 v48, v48, v201
	v_mul_f32_e32 v49, v49, v201
	v_mul_f32_e32 v42, v42, v201
	v_mul_f32_e32 v43, v43, v201
	v_mul_f32_e32 v44, v44, v201
	v_mul_f32_e32 v45, v45, v201
	v_max_f32_e32 v46, 0, v46
	v_max_f32_e32 v47, 0, v47
	v_max_f32_e32 v48, 0, v48
	v_max_f32_e32 v49, 0, v49
	v_max_f32_e32 v42, 0, v42
	v_max_f32_e32 v43, 0, v43
	v_max_f32_e32 v44, 0, v44
	v_max_f32_e32 v45, 0, v45
	v_pk_mul_f32 v[46:47], v[46:47], v[46:47]
	v_pk_mul_f32 v[48:49], v[48:49], v[48:49]
	v_pk_mul_f32 v[42:43], v[42:43], v[42:43]
	v_pk_mul_f32 v[44:45], v[44:45], v[44:45]
	v_cvt_pk_bf16_f32 v46, v46, v47
	v_cvt_pk_bf16_f32 v47, v48, v49
	v_cvt_pk_bf16_f32 v48, v42, v43
	v_cvt_pk_bf16_f32 v49, v44, v45
	global_store_dwordx4 v207, v[46:49], s[94:95]
	v_mul_f32_e32 v38, v38, v201
	v_mul_f32_e32 v39, v39, v201
	v_mul_f32_e32 v40, v40, v201
	v_mul_f32_e32 v41, v41, v201
	v_mul_f32_e32 v34, v34, v201
	v_mul_f32_e32 v35, v35, v201
	v_mul_f32_e32 v36, v36, v201
	v_mul_f32_e32 v37, v37, v201
	v_max_f32_e32 v38, 0, v38
	v_max_f32_e32 v39, 0, v39
	v_max_f32_e32 v40, 0, v40
	v_max_f32_e32 v41, 0, v41
	v_max_f32_e32 v34, 0, v34
	v_max_f32_e32 v35, 0, v35
	v_max_f32_e32 v36, 0, v36
	v_max_f32_e32 v37, 0, v37
	v_pk_mul_f32 v[38:39], v[38:39], v[38:39]
	v_pk_mul_f32 v[40:41], v[40:41], v[40:41]
	v_pk_mul_f32 v[34:35], v[34:35], v[34:35]
	v_pk_mul_f32 v[36:37], v[36:37], v[36:37]
	v_cvt_pk_bf16_f32 v38, v38, v39
	v_cvt_pk_bf16_f32 v39, v40, v41
	v_cvt_pk_bf16_f32 v40, v34, v35
	v_cvt_pk_bf16_f32 v41, v36, v37
	global_store_dwordx4 v207, v[38:41], s[94:95] offset:256
	v_add_u32_e32 v207, 0x280000, v205
	v_mul_f32_e32 v30, v30, v202
	v_mul_f32_e32 v31, v31, v202
	v_mul_f32_e32 v32, v32, v202
	v_mul_f32_e32 v33, v33, v202
	v_mul_f32_e32 v26, v26, v202
	v_mul_f32_e32 v27, v27, v202
	v_mul_f32_e32 v28, v28, v202
	v_mul_f32_e32 v29, v29, v202
	v_max_f32_e32 v30, 0, v30
	v_max_f32_e32 v31, 0, v31
	v_max_f32_e32 v32, 0, v32
	v_max_f32_e32 v33, 0, v33
	v_max_f32_e32 v26, 0, v26
	v_max_f32_e32 v27, 0, v27
	v_max_f32_e32 v28, 0, v28
	v_max_f32_e32 v29, 0, v29
	v_pk_mul_f32 v[30:31], v[30:31], v[30:31]
	v_pk_mul_f32 v[32:33], v[32:33], v[32:33]
	v_pk_mul_f32 v[26:27], v[26:27], v[26:27]
	v_pk_mul_f32 v[28:29], v[28:29], v[28:29]
	v_cvt_pk_bf16_f32 v30, v30, v31
	v_cvt_pk_bf16_f32 v31, v32, v33
	v_cvt_pk_bf16_f32 v32, v26, v27
	v_cvt_pk_bf16_f32 v33, v28, v29
	global_store_dwordx4 v207, v[30:33], s[94:95]
	v_mul_f32_e32 v22, v22, v202
	v_mul_f32_e32 v23, v23, v202
	v_mul_f32_e32 v24, v24, v202
	v_mul_f32_e32 v25, v25, v202
	v_mul_f32_e32 v18, v18, v202
	v_mul_f32_e32 v19, v19, v202
	v_mul_f32_e32 v20, v20, v202
	v_mul_f32_e32 v21, v21, v202
	v_max_f32_e32 v22, 0, v22
	v_max_f32_e32 v23, 0, v23
	v_max_f32_e32 v24, 0, v24
	v_max_f32_e32 v25, 0, v25
	v_max_f32_e32 v18, 0, v18
	v_max_f32_e32 v19, 0, v19
	v_max_f32_e32 v20, 0, v20
	v_max_f32_e32 v21, 0, v21
	v_pk_mul_f32 v[22:23], v[22:23], v[22:23]
	v_pk_mul_f32 v[24:25], v[24:25], v[24:25]
	v_pk_mul_f32 v[18:19], v[18:19], v[18:19]
	v_pk_mul_f32 v[20:21], v[20:21], v[20:21]
	v_cvt_pk_bf16_f32 v22, v22, v23
	v_cvt_pk_bf16_f32 v23, v24, v25
	v_cvt_pk_bf16_f32 v24, v18, v19
	v_cvt_pk_bf16_f32 v25, v20, v21
	global_store_dwordx4 v207, v[22:25], s[94:95] offset:256
	v_add_u32_e32 v207, 0x2c0000, v205
	v_mul_f32_e32 v14, v14, v203
	v_mul_f32_e32 v15, v15, v203
	v_mul_f32_e32 v16, v16, v203
	v_mul_f32_e32 v17, v17, v203
	v_mul_f32_e32 v10, v10, v203
	v_mul_f32_e32 v11, v11, v203
	v_mul_f32_e32 v12, v12, v203
	v_mul_f32_e32 v13, v13, v203
	v_max_f32_e32 v14, 0, v14
	v_max_f32_e32 v15, 0, v15
	v_max_f32_e32 v16, 0, v16
	v_max_f32_e32 v17, 0, v17
	v_max_f32_e32 v10, 0, v10
	v_max_f32_e32 v11, 0, v11
	v_max_f32_e32 v12, 0, v12
	v_max_f32_e32 v13, 0, v13
	v_pk_mul_f32 v[14:15], v[14:15], v[14:15]
	v_pk_mul_f32 v[16:17], v[16:17], v[16:17]
	v_pk_mul_f32 v[10:11], v[10:11], v[10:11]
	v_pk_mul_f32 v[12:13], v[12:13], v[12:13]
	v_cvt_pk_bf16_f32 v14, v14, v15
	v_cvt_pk_bf16_f32 v15, v16, v17
	v_cvt_pk_bf16_f32 v16, v10, v11
	v_cvt_pk_bf16_f32 v17, v12, v13
	global_store_dwordx4 v207, v[14:17], s[94:95]
	v_mul_f32_e32 v6, v6, v203
	v_mul_f32_e32 v7, v7, v203
	v_mul_f32_e32 v8, v8, v203
	v_mul_f32_e32 v9, v9, v203
	v_mul_f32_e32 v2, v2, v203
	v_mul_f32_e32 v3, v3, v203
	v_mul_f32_e32 v4, v4, v203
	v_mul_f32_e32 v5, v5, v203
	v_max_f32_e32 v6, 0, v6
	v_max_f32_e32 v7, 0, v7
	v_max_f32_e32 v8, 0, v8
	v_max_f32_e32 v9, 0, v9
	v_max_f32_e32 v2, 0, v2
	v_max_f32_e32 v3, 0, v3
	v_max_f32_e32 v4, 0, v4
	v_max_f32_e32 v5, 0, v5
	v_pk_mul_f32 v[6:7], v[6:7], v[6:7]
	v_pk_mul_f32 v[8:9], v[8:9], v[8:9]
	v_pk_mul_f32 v[2:3], v[2:3], v[2:3]
	v_pk_mul_f32 v[4:5], v[4:5], v[4:5]
	v_cvt_pk_bf16_f32 v6, v6, v7
	v_cvt_pk_bf16_f32 v7, v8, v9
	v_cvt_pk_bf16_f32 v8, v2, v3
	v_cvt_pk_bf16_f32 v9, v4, v5
	global_store_dwordx4 v207, v[6:9], s[94:95] offset:256
	s_mov_b64 s[6:7], -1
	s_andn2_b64 vcc, exec, s[4:5]
	s_cbranch_vccnz .LBB0_488
	s_andn2_b64 vcc, exec, s[8:9]
	s_cbranch_vccnz .LBB0_487
	s_barrier
	s_branch .LBB0_487
